# MLA attention: static s_setprio 1 for waves 4-7 during a unit, on top of write-through 16-byte stores
# speedup vs baseline: 1.0117x; 1.0064x over previous
; #define SBAR() __builtin_amdgcn_sched_barrier(0)
; __device__ __forceinline__ int crow(int r, int hi) { return (r & 3) + 8 * (r >> 2) + 4 * hi; }
; __device__ __forceinline__ void mla_unit(char* lds, const bf16_t* __restrict__ Qp, const bf16_t* __restrict__ Knp, const bf16_t* __restrict__ Vp, ...
;     ...
;   if (hi == 0) li_l[r32] = l_reg; asm volatile("s_waitcnt lgkmcnt(0)" ::: "memory");
;   float rli[16];
; #pragma unroll
;   for (int r = 0; r < 16; ++r) rli[r] = __builtin_amdgcn_rcpf(li_l[crow(r, hi)]);
;   { unsigned zr[16][4];
; #pragma unroll
;     for (int r = 0; r < 16; ++r) { const long trow = wid * QBLK + crow(r, hi);
; #pragma unroll
;       for (int d0 = 0; d0 < 4; ++d0) zr[r][d0] = Zp[trow * LDZ + d0 * 32 + r32]; }
;     asm volatile("s_waitcnt vmcnt(0)" ::: "memory"); SBAR();
.LBB0_235:
	s_or_b64 exec, exec, s[6:7]
	s_waitcnt lgkmcnt(0)
	ds_read_b128 v[66:69], v90
	ds_read_b128 v[70:73], v90 offset:32
	s_lshl_b32 s0, s38, 22
	s_and_b32 s0, s0, 0x3800000
	s_add_u32 s5, s90, s0
	s_waitcnt lgkmcnt(1)
	v_rcp_f32_e32 v171, v66
	v_rcp_f32_e32 v166, v67
	v_rcp_f32_e32 v161, v68
	v_rcp_f32_e32 v155, v69
	ds_read_b128 v[66:69], v90 offset:64
	s_addc_u32 s6, s91, 0
	s_lshl_b64 s[0:1], s[64:65], 9
	s_add_u32 s0, s5, s0
	s_addc_u32 s1, s6, s1
	s_lshl_b32 s5, s69, 8
	s_and_b32 s5, s5, 0x100
	s_add_u32 s6, s0, s5
	s_waitcnt lgkmcnt(0)
	v_rcp_f32_e32 v128, v66
	v_rcp_f32_e32 v122, v67
	v_rcp_f32_e32 v117, v68
	v_rcp_f32_e32 v111, v69
	ds_read_b128 v[66:69], v90 offset:96
	s_addc_u32 s7, s1, 0
	s_lshl_b32 s0, s38, 15
	s_add_u32 s0, s64, s0
	s_addc_u32 s1, s65, 0
	s_lshl_b64 s[0:1], s[0:1], 7
	s_add_u32 s40, s28, s0
	s_waitcnt lgkmcnt(0)
	v_rcp_f32_e32 v105, v66
	v_rcp_f32_e32 v103, v67
	v_or_b32_e32 v98, s39, v195
	v_lshlrev_b32_e32 v66, 1, v196
	v_mov_b32_e32 v67, v0
	s_addc_u32 s41, s29, s1
	v_rcp_f32_e32 v102, v68
	v_rcp_f32_e32 v1, v69
	v_lshl_add_u64 v[68:69], s[6:7], 0, v[66:67]
	s_mov_b64 s[0:1], 0x2000000
	v_ashrrev_i32_e32 v99, 31, v98
	v_lshl_add_u64 v[100:101], v[68:69], 0, s[0:1]
	v_lshlrev_b64 v[68:69], 9, v[98:99]
	v_or_b32_e32 v96, 1, v98
	v_lshl_add_u64 v[68:69], v[100:101], 0, v[68:69]
	v_ashrrev_i32_e32 v97, 31, v96
	global_load_ushort v180, v[68:69], off
	global_load_ushort v177, v[68:69], off offset:64
	global_load_ushort v176, v[68:69], off offset:128
	global_load_ushort v175, v[68:69], off offset:192
	v_lshlrev_b64 v[68:69], 9, v[96:97]
	v_or_b32_e32 v94, 2, v98
	v_lshl_add_u64 v[68:69], v[100:101], 0, v[68:69]
	v_ashrrev_i32_e32 v95, 31, v94
	global_load_ushort v174, v[68:69], off
	global_load_ushort v173, v[68:69], off offset:64
	global_load_ushort v172, v[68:69], off offset:128
	global_load_ushort v170, v[68:69], off offset:192
	v_lshlrev_b64 v[68:69], 9, v[94:95]
	v_or_b32_e32 v92, 3, v98
	v_lshl_add_u64 v[68:69], v[100:101], 0, v[68:69]
	v_ashrrev_i32_e32 v93, 31, v92
	global_load_ushort v169, v[68:69], off
	global_load_ushort v168, v[68:69], off offset:64
	global_load_ushort v167, v[68:69], off offset:128
	global_load_ushort v165, v[68:69], off offset:192
	v_lshlrev_b64 v[68:69], 9, v[92:93]
	v_or_b32_e32 v90, 8, v98
	v_lshl_add_u64 v[68:69], v[100:101], 0, v[68:69]
	v_ashrrev_i32_e32 v91, 31, v90
	global_load_ushort v164, v[68:69], off
	global_load_ushort v163, v[68:69], off offset:64
	global_load_ushort v162, v[68:69], off offset:128
	global_load_ushort v160, v[68:69], off offset:192
	v_lshlrev_b64 v[68:69], 9, v[90:91]
	v_or_b32_e32 v88, 9, v98
	v_lshl_add_u64 v[68:69], v[100:101], 0, v[68:69]
	v_ashrrev_i32_e32 v89, 31, v88
	global_load_ushort v159, v[68:69], off
	global_load_ushort v158, v[68:69], off offset:64
	global_load_ushort v157, v[68:69], off offset:128
	global_load_ushort v156, v[68:69], off offset:192
	v_lshlrev_b64 v[68:69], 9, v[88:89]
	v_or_b32_e32 v86, 10, v98
	v_lshl_add_u64 v[68:69], v[100:101], 0, v[68:69]
	v_ashrrev_i32_e32 v87, 31, v86
	global_load_ushort v154, v[68:69], off
	global_load_ushort v153, v[68:69], off offset:64
	global_load_ushort v152, v[68:69], off offset:128
	global_load_ushort v151, v[68:69], off offset:192
	v_lshlrev_b64 v[68:69], 9, v[86:87]
	v_or_b32_e32 v84, 11, v98
	v_lshl_add_u64 v[68:69], v[100:101], 0, v[68:69]
	v_ashrrev_i32_e32 v85, 31, v84
	global_load_ushort v149, v[68:69], off
	global_load_ushort v148, v[68:69], off offset:64
	global_load_ushort v147, v[68:69], off offset:128
	global_load_ushort v146, v[68:69], off offset:192
	v_lshlrev_b64 v[68:69], 9, v[84:85]
	v_or_b32_e32 v82, 16, v98
	v_lshl_add_u64 v[68:69], v[100:101], 0, v[68:69]
	v_ashrrev_i32_e32 v83, 31, v82
	global_load_ushort v145, v[68:69], off
	global_load_ushort v143, v[68:69], off offset:64
	global_load_ushort v142, v[68:69], off offset:128
	global_load_ushort v141, v[68:69], off offset:192
	v_lshlrev_b64 v[68:69], 9, v[82:83]
	v_or_b32_e32 v80, 17, v98
	v_lshl_add_u64 v[68:69], v[100:101], 0, v[68:69]
	v_ashrrev_i32_e32 v81, 31, v80
	global_load_ushort v140, v[68:69], off
	global_load_ushort v138, v[68:69], off offset:64
	global_load_ushort v137, v[68:69], off offset:128
	global_load_ushort v136, v[68:69], off offset:192
	v_lshlrev_b64 v[68:69], 9, v[80:81]
	v_or_b32_e32 v78, 18, v98
	v_lshl_add_u64 v[68:69], v[100:101], 0, v[68:69]
	v_ashrrev_i32_e32 v79, 31, v78
	global_load_ushort v135, v[68:69], off
	global_load_ushort v134, v[68:69], off offset:64
	global_load_ushort v132, v[68:69], off offset:128
	global_load_ushort v131, v[68:69], off offset:192
	v_lshlrev_b64 v[68:69], 9, v[78:79]
	v_or_b32_e32 v76, 19, v98
	v_lshl_add_u64 v[68:69], v[100:101], 0, v[68:69]
	v_ashrrev_i32_e32 v77, 31, v76
	global_load_ushort v130, v[68:69], off
	global_load_ushort v129, v[68:69], off offset:64
	global_load_ushort v127, v[68:69], off offset:128
	global_load_ushort v126, v[68:69], off offset:192
	v_lshlrev_b64 v[68:69], 9, v[76:77]
	v_or_b32_e32 v74, 24, v98
	v_lshl_add_u64 v[68:69], v[100:101], 0, v[68:69]
	v_ashrrev_i32_e32 v75, 31, v74
	v_rcp_f32_e32 v139, v72
	global_load_ushort v125, v[68:69], off
	global_load_ushort v124, v[68:69], off offset:64
	global_load_ushort v123, v[68:69], off offset:128
	global_load_ushort v121, v[68:69], off offset:192
	v_lshlrev_b64 v[68:69], 9, v[74:75]
	v_or_b32_e32 v72, 25, v98
	v_rcp_f32_e32 v133, v73
	v_lshl_add_u64 v[68:69], v[100:101], 0, v[68:69]
	v_ashrrev_i32_e32 v73, 31, v72
	v_rcp_f32_e32 v150, v70
	global_load_ushort v120, v[68:69], off
	global_load_ushort v119, v[68:69], off offset:64
	global_load_ushort v118, v[68:69], off offset:128
	global_load_ushort v116, v[68:69], off offset:192
	v_lshlrev_b64 v[68:69], 9, v[72:73]
	v_or_b32_e32 v70, 26, v98
	v_rcp_f32_e32 v144, v71
	v_lshl_add_u64 v[68:69], v[100:101], 0, v[68:69]
	v_ashrrev_i32_e32 v71, 31, v70
	global_load_ushort v115, v[68:69], off
	global_load_ushort v114, v[68:69], off offset:64
	global_load_ushort v113, v[68:69], off offset:128
	global_load_ushort v112, v[68:69], off offset:192
	v_lshlrev_b64 v[68:69], 9, v[70:71]
	v_lshl_add_u64 v[68:69], v[100:101], 0, v[68:69]
	global_load_ushort v110, v[68:69], off
	global_load_ushort v109, v[68:69], off offset:64
	global_load_ushort v108, v[68:69], off offset:128
	global_load_ushort v107, v[68:69], off offset:192
	v_or_b32_e32 v68, 27, v98
	v_ashrrev_i32_e32 v69, 31, v68
	v_lshlrev_b64 v[178:179], 9, v[68:69]
	v_lshl_add_u64 v[178:179], v[100:101], 0, v[178:179]
	global_load_ushort v106, v[178:179], off
	global_load_ushort v104, v[178:179], off offset:64
	global_load_ushort v101, v[178:179], off offset:128
	global_load_ushort v100, v[178:179], off offset:192
	s_waitcnt vmcnt(0)
; __device__ __forceinline__ float bf2f(unsigned h) { return __uint_as_float(h << 16); }
; __device__ __forceinline__ unsigned f2bf(float f) { unsigned u = __float_as_uint(f); return (u + 0x7fffu + ((u >> 16) & 1u)) >> 16; }
; __device__ __forceinline__ int crow(int r, int hi) { return (r & 3) + 8 * (r >> 2) + 4 * hi; }
; __device__ __forceinline__ void mla_unit(char* lds, const bf16_t* __restrict__ Qp, const bf16_t* __restrict__ Knp, const bf16_t* __restrict__ Vp, ...
;     ...
;     for (int r = 0; r < 16; ++r) { const long trow = wid * QBLK + crow(r, hi);
; #pragma unroll
;       for (int d0 = 0; d0 < 4; ++d0) { const float z = bf2f(zr[r][d0]); const float v = o[d0][r] * rli[r];
;         const float g = v * z * __builtin_amdgcn_rcpf(1.f + __expf(-z));
;         Op[((size_t)(d0 >> 1) * M_TOK + trow) * 64 + (d0 & 1) * 32 + r32] = (bf16_t)f2bf(g); } } }
	s_waitcnt vmcnt(62)
	v_lshlrev_b32_e32 v178, 16, v180
	v_mul_f32_e32 v50, v50, v171
	v_mul_f32_e32 v50, v50, v178
	v_mul_f32_e32 v178, 0xbfb8aa3b, v178
	v_exp_f32_e32 v178, v178
	v_lshlrev_b64 v[98:99], 7, v[98:99]
	v_lshl_add_u64 v[98:99], s[40:41], 0, v[98:99]
	v_lshl_add_u64 v[98:99], v[98:99], 0, v[66:67]
	v_add_f32_e32 v178, 1.0, v178
	v_rcp_f32_e32 v178, v178
	v_mul_f32_e32 v34, v34, v171
	v_mul_f32_e32 v18, v18, v171
	v_mul_f32_e32 v2, v2, v171
	v_mul_f32_e32 v50, v50, v178
	v_bfe_u32 v178, v50, 16, 1
	v_add3_u32 v50, v50, v178, s63
	global_store_short_d16_hi v[98:99], v50, off
	v_lshlrev_b32_e32 v50, 16, v177
	v_mul_f32_e32 v34, v34, v50
	v_mul_f32_e32 v50, 0xbfb8aa3b, v50
	v_exp_f32_e32 v50, v50
	v_mul_f32_e32 v3, v3, v166
	v_mul_f32_e32 v4, v4, v161
	v_mul_f32_e32 v5, v5, v155
	v_add_f32_e32 v50, 1.0, v50
	v_rcp_f32_e32 v50, v50
	s_mov_b32 s74, s8
	v_mul_f32_e32 v34, v34, v50
	v_bfe_u32 v50, v34, 16, 1
	v_add3_u32 v34, v34, v50, s63
	global_store_short_d16_hi v[98:99], v34, off offset:64
	s_waitcnt vmcnt(62)
	v_lshlrev_b32_e32 v34, 16, v176
	v_mul_f32_e32 v18, v18, v34
	v_mul_f32_e32 v34, 0xbfb8aa3b, v34
	v_exp_f32_e32 v34, v34
	v_add_co_u32_e32 v98, vcc, s93, v98
	v_add_f32_e32 v34, 1.0, v34
	v_rcp_f32_e32 v34, v34
	v_addc_co_u32_e32 v99, vcc, 0, v99, vcc
	v_mul_f32_e32 v18, v18, v34
	v_bfe_u32 v34, v18, 16, 1
	v_add3_u32 v18, v18, v34, s63
	global_store_short_d16_hi v[98:99], v18, off
	v_lshlrev_b32_e32 v18, 16, v175
	v_mul_f32_e32 v2, v2, v18
	v_mul_f32_e32 v18, 0xbfb8aa3b, v18
	v_exp_f32_e32 v18, v18
	s_nop 0
	v_add_f32_e32 v18, 1.0, v18
	v_rcp_f32_e32 v18, v18
	s_nop 0
	v_mul_f32_e32 v2, v2, v18
	v_bfe_u32 v18, v2, 16, 1
	v_add3_u32 v2, v2, v18, s63
	global_store_short_d16_hi v[98:99], v2, off offset:64
	s_waitcnt vmcnt(62)
	v_lshlrev_b32_e32 v2, 16, v174
	v_mul_f32_e32 v18, v51, v166
	v_mul_f32_e32 v18, v18, v2
	v_mul_f32_e32 v2, 0xbfb8aa3b, v2
	v_exp_f32_e32 v2, v2
	v_lshlrev_b64 v[50:51], 7, v[96:97]
	v_lshl_add_u64 v[50:51], s[40:41], 0, v[50:51]
	v_lshl_add_u64 v[50:51], v[50:51], 0, v[66:67]
	v_add_f32_e32 v2, 1.0, v2
	v_rcp_f32_e32 v2, v2
	s_nop 0
	v_mul_f32_e32 v2, v18, v2
	v_bfe_u32 v18, v2, 16, 1
	v_add3_u32 v2, v2, v18, s63
	global_store_short_d16_hi v[50:51], v2, off
	v_lshlrev_b32_e32 v2, 16, v173
	v_mul_f32_e32 v18, v35, v166
	v_mul_f32_e32 v18, v18, v2
	v_mul_f32_e32 v2, 0xbfb8aa3b, v2
	v_exp_f32_e32 v2, v2
	s_nop 0
	v_add_f32_e32 v2, 1.0, v2
	v_rcp_f32_e32 v2, v2
	s_nop 0
	v_mul_f32_e32 v2, v18, v2
	v_bfe_u32 v18, v2, 16, 1
	v_add3_u32 v2, v2, v18, s63
	global_store_short_d16_hi v[50:51], v2, off offset:64
	s_waitcnt vmcnt(62)
	v_lshlrev_b32_e32 v2, 16, v172
	v_mul_f32_e32 v18, v19, v166
	v_mul_f32_e32 v18, v18, v2
	v_mul_f32_e32 v2, 0xbfb8aa3b, v2
	v_exp_f32_e32 v2, v2
	s_nop 0
	v_add_f32_e32 v2, 1.0, v2
	v_rcp_f32_e32 v2, v2
	s_nop 0
	v_mul_f32_e32 v2, v18, v2
	v_bfe_u32 v18, v2, 16, 1
	v_add3_u32 v2, v2, v18, s63
	v_add_co_u32_e32 v18, vcc, s93, v50
	s_nop 1
	v_addc_co_u32_e32 v19, vcc, 0, v51, vcc
	global_store_short_d16_hi v[18:19], v2, off
	v_lshlrev_b32_e32 v2, 16, v170
	v_mul_f32_e32 v3, v3, v2
	v_mul_f32_e32 v2, 0xbfb8aa3b, v2
	v_exp_f32_e32 v2, v2
	s_nop 0
	v_add_f32_e32 v2, 1.0, v2
	v_rcp_f32_e32 v2, v2
	s_nop 0
	v_mul_f32_e32 v2, v3, v2
	v_bfe_u32 v3, v2, 16, 1
	v_add3_u32 v2, v2, v3, s63
	global_store_short_d16_hi v[18:19], v2, off offset:64
	s_waitcnt vmcnt(62)
	v_lshlrev_b32_e32 v2, 16, v169
	v_mul_f32_e32 v3, v52, v161
	v_mul_f32_e32 v3, v3, v2
	v_mul_f32_e32 v2, 0xbfb8aa3b, v2
	v_exp_f32_e32 v2, v2
	v_mul_f32_e32 v19, v36, v161
	v_add_f32_e32 v2, 1.0, v2
	v_rcp_f32_e32 v2, v2
	s_nop 0
	v_mul_f32_e32 v2, v3, v2
	v_bfe_u32 v3, v2, 16, 1
	v_add3_u32 v18, v2, v3, s63
	v_lshlrev_b64 v[2:3], 7, v[94:95]
	v_lshl_add_u64 v[2:3], s[40:41], 0, v[2:3]
	v_lshl_add_u64 v[2:3], v[2:3], 0, v[66:67]
	global_store_short_d16_hi v[2:3], v18, off
	v_lshlrev_b32_e32 v18, 16, v168
	v_mul_f32_e32 v19, v19, v18
	v_mul_f32_e32 v18, 0xbfb8aa3b, v18
	v_exp_f32_e32 v18, v18
	s_nop 0
	v_add_f32_e32 v18, 1.0, v18
	v_rcp_f32_e32 v18, v18
	s_nop 0
	v_mul_f32_e32 v18, v19, v18
	v_bfe_u32 v19, v18, 16, 1
	v_add3_u32 v18, v18, v19, s63
	global_store_short_d16_hi v[2:3], v18, off offset:64
	s_waitcnt vmcnt(62)
	v_lshlrev_b32_e32 v18, 16, v167
	v_mul_f32_e32 v19, v20, v161
	v_mul_f32_e32 v19, v19, v18
	v_mul_f32_e32 v18, 0xbfb8aa3b, v18
	v_exp_f32_e32 v18, v18
	v_add_co_u32_e32 v2, vcc, s93, v2
	v_add_f32_e32 v18, 1.0, v18
	v_rcp_f32_e32 v18, v18
	v_addc_co_u32_e32 v3, vcc, 0, v3, vcc
	v_mul_f32_e32 v18, v19, v18
	v_bfe_u32 v19, v18, 16, 1
	v_add3_u32 v18, v18, v19, s63
	global_store_short_d16_hi v[2:3], v18, off
	v_lshlrev_b32_e32 v18, 16, v165
	v_mul_f32_e32 v4, v4, v18
	v_mul_f32_e32 v18, 0xbfb8aa3b, v18
	v_exp_f32_e32 v18, v18
	s_nop 0
	v_add_f32_e32 v18, 1.0, v18
	v_rcp_f32_e32 v18, v18
	s_nop 0
	v_mul_f32_e32 v4, v4, v18
	v_bfe_u32 v18, v4, 16, 1
	v_add3_u32 v4, v4, v18, s63
	global_store_short_d16_hi v[2:3], v4, off offset:64
	s_waitcnt vmcnt(62)
	v_lshlrev_b32_e32 v2, 16, v164
	v_mul_f32_e32 v3, v53, v155
	v_mul_f32_e32 v3, v3, v2
	v_mul_f32_e32 v2, 0xbfb8aa3b, v2
	v_exp_f32_e32 v2, v2
	v_mul_f32_e32 v18, v37, v155
	v_add_f32_e32 v2, 1.0, v2
	v_rcp_f32_e32 v2, v2
	s_nop 0
	v_mul_f32_e32 v2, v3, v2
	v_bfe_u32 v3, v2, 16, 1
	v_add3_u32 v4, v2, v3, s63
	v_lshlrev_b64 v[2:3], 7, v[92:93]
	v_lshl_add_u64 v[2:3], s[40:41], 0, v[2:3]
	v_lshl_add_u64 v[2:3], v[2:3], 0, v[66:67]
	global_store_short_d16_hi v[2:3], v4, off
	v_lshlrev_b32_e32 v4, 16, v163
	v_mul_f32_e32 v18, v18, v4
	v_mul_f32_e32 v4, 0xbfb8aa3b, v4
	v_exp_f32_e32 v4, v4
	s_nop 0
	v_add_f32_e32 v4, 1.0, v4
	v_rcp_f32_e32 v4, v4
	s_nop 0
	v_mul_f32_e32 v4, v18, v4
	v_bfe_u32 v18, v4, 16, 1
	v_add3_u32 v4, v4, v18, s63
	global_store_short_d16_hi v[2:3], v4, off offset:64
	s_waitcnt vmcnt(62)
; __device__ __forceinline__ float bf2f(unsigned h) { return __uint_as_float(h << 16); }
; __device__ __forceinline__ unsigned f2bf(float f) { unsigned u = __float_as_uint(f); return (u + 0x7fffu + ((u >> 16) & 1u)) >> 16; }
; __device__ __forceinline__ int crow(int r, int hi) { return (r & 3) + 8 * (r >> 2) + 4 * hi; }
; __device__ __forceinline__ void mla_unit(char* lds, const bf16_t* __restrict__ Qp, const bf16_t* __restrict__ Knp, const bf16_t* __restrict__ Vp, ...
;     ...
;     for (int r = 0; r < 16; ++r) { const long trow = wid * QBLK + crow(r, hi);
; #pragma unroll
;       for (int d0 = 0; d0 < 4; ++d0) { const float z = bf2f(zr[r][d0]); const float v = o[d0][r] * rli[r];
;         const float g = v * z * __builtin_amdgcn_rcpf(1.f + __expf(-z));
;         Op[((size_t)(d0 >> 1) * M_TOK + trow) * 64 + (d0 & 1) * 32 + r32] = (bf16_t)f2bf(g); } } }
	v_lshlrev_b32_e32 v4, 16, v162
	v_mul_f32_e32 v18, v21, v155
	v_mul_f32_e32 v18, v18, v4
	v_mul_f32_e32 v4, 0xbfb8aa3b, v4
	v_exp_f32_e32 v4, v4
	v_add_co_u32_e32 v2, vcc, s93, v2
	v_add_f32_e32 v4, 1.0, v4
	v_rcp_f32_e32 v4, v4
	v_addc_co_u32_e32 v3, vcc, 0, v3, vcc
	v_mul_f32_e32 v4, v18, v4
	v_bfe_u32 v18, v4, 16, 1
	v_add3_u32 v4, v4, v18, s63
	global_store_short_d16_hi v[2:3], v4, off
	v_lshlrev_b32_e32 v4, 16, v160
	v_mul_f32_e32 v5, v5, v4
	v_mul_f32_e32 v4, 0xbfb8aa3b, v4
	v_exp_f32_e32 v4, v4
	s_nop 0
	v_add_f32_e32 v4, 1.0, v4
	v_rcp_f32_e32 v4, v4
	s_nop 0
	v_mul_f32_e32 v4, v5, v4
	v_bfe_u32 v5, v4, 16, 1
	v_add3_u32 v4, v4, v5, s63
	global_store_short_d16_hi v[2:3], v4, off offset:64
	s_waitcnt vmcnt(62)
	v_lshlrev_b32_e32 v2, 16, v159
	v_mul_f32_e32 v3, v54, v150
	v_mul_f32_e32 v3, v3, v2
	v_mul_f32_e32 v2, 0xbfb8aa3b, v2
	v_exp_f32_e32 v2, v2
	v_mul_f32_e32 v5, v38, v150
	v_add_f32_e32 v2, 1.0, v2
	v_rcp_f32_e32 v2, v2
	s_nop 0
	v_mul_f32_e32 v2, v3, v2
	v_bfe_u32 v3, v2, 16, 1
	v_add3_u32 v4, v2, v3, s63
	v_lshlrev_b64 v[2:3], 7, v[90:91]
	v_lshl_add_u64 v[2:3], s[40:41], 0, v[2:3]
	v_lshl_add_u64 v[2:3], v[2:3], 0, v[66:67]
	global_store_short_d16_hi v[2:3], v4, off
	v_lshlrev_b32_e32 v4, 16, v158
	v_mul_f32_e32 v5, v5, v4
	v_mul_f32_e32 v4, 0xbfb8aa3b, v4
	v_exp_f32_e32 v4, v4
	s_nop 0
	v_add_f32_e32 v4, 1.0, v4
	v_rcp_f32_e32 v4, v4
	s_nop 0
	v_mul_f32_e32 v4, v5, v4
	v_bfe_u32 v5, v4, 16, 1
	v_add3_u32 v4, v4, v5, s63
	global_store_short_d16_hi v[2:3], v4, off offset:64
	s_waitcnt vmcnt(62)
	v_lshlrev_b32_e32 v4, 16, v157
	v_mul_f32_e32 v5, v22, v150
	v_mul_f32_e32 v5, v5, v4
	v_mul_f32_e32 v4, 0xbfb8aa3b, v4
	v_exp_f32_e32 v4, v4
	v_add_co_u32_e32 v2, vcc, s93, v2
	v_add_f32_e32 v4, 1.0, v4
	v_rcp_f32_e32 v4, v4
	v_addc_co_u32_e32 v3, vcc, 0, v3, vcc
	v_mul_f32_e32 v4, v5, v4
	v_bfe_u32 v5, v4, 16, 1
	v_add3_u32 v4, v4, v5, s63
	global_store_short_d16_hi v[2:3], v4, off
	v_lshlrev_b32_e32 v4, 16, v156
	v_mul_f32_e32 v5, v6, v150
	v_mul_f32_e32 v5, v5, v4
	v_mul_f32_e32 v4, 0xbfb8aa3b, v4
	v_exp_f32_e32 v4, v4
	s_nop 0
	v_add_f32_e32 v4, 1.0, v4
	v_rcp_f32_e32 v4, v4
	s_nop 0
	v_mul_f32_e32 v4, v5, v4
	v_bfe_u32 v5, v4, 16, 1
	v_add3_u32 v4, v4, v5, s63
	global_store_short_d16_hi v[2:3], v4, off offset:64
	s_waitcnt vmcnt(62)
	v_lshlrev_b32_e32 v2, 16, v154
	v_mul_f32_e32 v3, v55, v144
	v_mul_f32_e32 v3, v3, v2
	v_mul_f32_e32 v2, 0xbfb8aa3b, v2
	v_exp_f32_e32 v2, v2
	v_mul_f32_e32 v5, v39, v144
	v_add_f32_e32 v2, 1.0, v2
	v_rcp_f32_e32 v2, v2
	s_nop 0
	v_mul_f32_e32 v2, v3, v2
	v_bfe_u32 v3, v2, 16, 1
	v_add3_u32 v4, v2, v3, s63
	v_lshlrev_b64 v[2:3], 7, v[88:89]
	v_lshl_add_u64 v[2:3], s[40:41], 0, v[2:3]
	v_lshl_add_u64 v[2:3], v[2:3], 0, v[66:67]
	global_store_short_d16_hi v[2:3], v4, off
	v_lshlrev_b32_e32 v4, 16, v153
	v_mul_f32_e32 v5, v5, v4
	v_mul_f32_e32 v4, 0xbfb8aa3b, v4
	v_exp_f32_e32 v4, v4
	s_nop 0
	v_add_f32_e32 v4, 1.0, v4
	v_rcp_f32_e32 v4, v4
	s_nop 0
	v_mul_f32_e32 v4, v5, v4
	v_bfe_u32 v5, v4, 16, 1
	v_add3_u32 v4, v4, v5, s63
	global_store_short_d16_hi v[2:3], v4, off offset:64
	s_waitcnt vmcnt(62)
	v_lshlrev_b32_e32 v4, 16, v152
	v_mul_f32_e32 v5, v23, v144
	v_mul_f32_e32 v5, v5, v4
	v_mul_f32_e32 v4, 0xbfb8aa3b, v4
	v_exp_f32_e32 v4, v4
	v_add_co_u32_e32 v2, vcc, s93, v2
	v_add_f32_e32 v4, 1.0, v4
	v_rcp_f32_e32 v4, v4
	v_addc_co_u32_e32 v3, vcc, 0, v3, vcc
	v_mul_f32_e32 v4, v5, v4
	v_bfe_u32 v5, v4, 16, 1
	v_add3_u32 v4, v4, v5, s63
	global_store_short_d16_hi v[2:3], v4, off
	v_lshlrev_b32_e32 v4, 16, v151
	v_mul_f32_e32 v5, v7, v144
	v_mul_f32_e32 v5, v5, v4
	v_mul_f32_e32 v4, 0xbfb8aa3b, v4
	v_exp_f32_e32 v4, v4
	s_nop 0
	v_add_f32_e32 v4, 1.0, v4
	v_rcp_f32_e32 v4, v4
	s_nop 0
	v_mul_f32_e32 v4, v5, v4
	v_bfe_u32 v5, v4, 16, 1
	v_add3_u32 v4, v4, v5, s63
	global_store_short_d16_hi v[2:3], v4, off offset:64
	s_waitcnt vmcnt(62)
	v_lshlrev_b32_e32 v2, 16, v149
	v_mul_f32_e32 v3, v56, v139
	v_mul_f32_e32 v3, v3, v2
	v_mul_f32_e32 v2, 0xbfb8aa3b, v2
	v_exp_f32_e32 v2, v2
	v_mul_f32_e32 v5, v40, v139
	v_add_f32_e32 v2, 1.0, v2
	v_rcp_f32_e32 v2, v2
	s_nop 0
	v_mul_f32_e32 v2, v3, v2
	v_bfe_u32 v3, v2, 16, 1
	v_add3_u32 v4, v2, v3, s63
	v_lshlrev_b64 v[2:3], 7, v[86:87]
	v_lshl_add_u64 v[2:3], s[40:41], 0, v[2:3]
	v_lshl_add_u64 v[2:3], v[2:3], 0, v[66:67]
	global_store_short_d16_hi v[2:3], v4, off
	v_lshlrev_b32_e32 v4, 16, v148
	v_mul_f32_e32 v5, v5, v4
	v_mul_f32_e32 v4, 0xbfb8aa3b, v4
	v_exp_f32_e32 v4, v4
	s_nop 0
	v_add_f32_e32 v4, 1.0, v4
	v_rcp_f32_e32 v4, v4
	s_nop 0
	v_mul_f32_e32 v4, v5, v4
	v_bfe_u32 v5, v4, 16, 1
	v_add3_u32 v4, v4, v5, s63
	global_store_short_d16_hi v[2:3], v4, off offset:64
	s_waitcnt vmcnt(62)
	v_lshlrev_b32_e32 v4, 16, v147
	v_mul_f32_e32 v5, v24, v139
	v_mul_f32_e32 v5, v5, v4
	v_mul_f32_e32 v4, 0xbfb8aa3b, v4
	v_exp_f32_e32 v4, v4
	v_add_co_u32_e32 v2, vcc, s93, v2
	v_add_f32_e32 v4, 1.0, v4
	v_rcp_f32_e32 v4, v4
	v_addc_co_u32_e32 v3, vcc, 0, v3, vcc
	v_mul_f32_e32 v4, v5, v4
	v_bfe_u32 v5, v4, 16, 1
	v_add3_u32 v4, v4, v5, s63
	global_store_short_d16_hi v[2:3], v4, off
	v_lshlrev_b32_e32 v4, 16, v146
	v_mul_f32_e32 v5, v8, v139
	v_mul_f32_e32 v5, v5, v4
	v_mul_f32_e32 v4, 0xbfb8aa3b, v4
	v_exp_f32_e32 v4, v4
	s_nop 0
	v_add_f32_e32 v4, 1.0, v4
	v_rcp_f32_e32 v4, v4
	s_nop 0
	v_mul_f32_e32 v4, v5, v4
	v_bfe_u32 v5, v4, 16, 1
	v_add3_u32 v4, v4, v5, s63
	global_store_short_d16_hi v[2:3], v4, off offset:64
	s_waitcnt vmcnt(62)
; __device__ __forceinline__ float bf2f(unsigned h) { return __uint_as_float(h << 16); }
; __device__ __forceinline__ unsigned f2bf(float f) { unsigned u = __float_as_uint(f); return (u + 0x7fffu + ((u >> 16) & 1u)) >> 16; }
; __device__ __forceinline__ int crow(int r, int hi) { return (r & 3) + 8 * (r >> 2) + 4 * hi; }
; __device__ __forceinline__ void mla_unit(char* lds, const bf16_t* __restrict__ Qp, const bf16_t* __restrict__ Knp, const bf16_t* __restrict__ Vp, ...
;     ...
;     for (int r = 0; r < 16; ++r) { const long trow = wid * QBLK + crow(r, hi);
; #pragma unroll
;       for (int d0 = 0; d0 < 4; ++d0) { const float z = bf2f(zr[r][d0]); const float v = o[d0][r] * rli[r];
;         const float g = v * z * __builtin_amdgcn_rcpf(1.f + __expf(-z));
;         Op[((size_t)(d0 >> 1) * M_TOK + trow) * 64 + (d0 & 1) * 32 + r32] = (bf16_t)f2bf(g); } } }
	v_lshlrev_b32_e32 v2, 16, v145
	v_mul_f32_e32 v3, v57, v133
	v_mul_f32_e32 v3, v3, v2
	v_mul_f32_e32 v2, 0xbfb8aa3b, v2
	v_exp_f32_e32 v2, v2
	v_mul_f32_e32 v5, v41, v133
	v_add_f32_e32 v2, 1.0, v2
	v_rcp_f32_e32 v2, v2
	s_nop 0
	v_mul_f32_e32 v2, v3, v2
	v_bfe_u32 v3, v2, 16, 1
	v_add3_u32 v4, v2, v3, s63
	v_lshlrev_b64 v[2:3], 7, v[84:85]
	v_lshl_add_u64 v[2:3], s[40:41], 0, v[2:3]
	v_lshl_add_u64 v[2:3], v[2:3], 0, v[66:67]
	global_store_short_d16_hi v[2:3], v4, off
	v_lshlrev_b32_e32 v4, 16, v143
	v_mul_f32_e32 v5, v5, v4
	v_mul_f32_e32 v4, 0xbfb8aa3b, v4
	v_exp_f32_e32 v4, v4
	s_nop 0
	v_add_f32_e32 v4, 1.0, v4
	v_rcp_f32_e32 v4, v4
	s_nop 0
	v_mul_f32_e32 v4, v5, v4
	v_bfe_u32 v5, v4, 16, 1
	v_add3_u32 v4, v4, v5, s63
	global_store_short_d16_hi v[2:3], v4, off offset:64
	s_waitcnt vmcnt(62)
	v_lshlrev_b32_e32 v4, 16, v142
	v_mul_f32_e32 v5, v25, v133
	v_mul_f32_e32 v5, v5, v4
	v_mul_f32_e32 v4, 0xbfb8aa3b, v4
	v_exp_f32_e32 v4, v4
	v_add_co_u32_e32 v2, vcc, s93, v2
	v_add_f32_e32 v4, 1.0, v4
	v_rcp_f32_e32 v4, v4
	v_addc_co_u32_e32 v3, vcc, 0, v3, vcc
	v_mul_f32_e32 v4, v5, v4
	v_bfe_u32 v5, v4, 16, 1
	v_add3_u32 v4, v4, v5, s63
	global_store_short_d16_hi v[2:3], v4, off
	v_lshlrev_b32_e32 v4, 16, v141
	v_mul_f32_e32 v5, v9, v133
	v_mul_f32_e32 v5, v5, v4
	v_mul_f32_e32 v4, 0xbfb8aa3b, v4
	v_exp_f32_e32 v4, v4
	s_nop 0
	v_add_f32_e32 v4, 1.0, v4
	v_rcp_f32_e32 v4, v4
	s_nop 0
	v_mul_f32_e32 v4, v5, v4
	v_bfe_u32 v5, v4, 16, 1
	v_add3_u32 v4, v4, v5, s63
	global_store_short_d16_hi v[2:3], v4, off offset:64
	s_waitcnt vmcnt(62)
	v_lshlrev_b32_e32 v2, 16, v140
	v_mul_f32_e32 v3, v58, v128
	v_mul_f32_e32 v3, v3, v2
	v_mul_f32_e32 v2, 0xbfb8aa3b, v2
	v_exp_f32_e32 v2, v2
	v_mul_f32_e32 v5, v42, v128
	v_add_f32_e32 v2, 1.0, v2
	v_rcp_f32_e32 v2, v2
	s_nop 0
	v_mul_f32_e32 v2, v3, v2
	v_bfe_u32 v3, v2, 16, 1
	v_add3_u32 v4, v2, v3, s63
	v_lshlrev_b64 v[2:3], 7, v[82:83]
	v_lshl_add_u64 v[2:3], s[40:41], 0, v[2:3]
	v_lshl_add_u64 v[2:3], v[2:3], 0, v[66:67]
	global_store_short_d16_hi v[2:3], v4, off
	v_lshlrev_b32_e32 v4, 16, v138
	v_mul_f32_e32 v5, v5, v4
	v_mul_f32_e32 v4, 0xbfb8aa3b, v4
	v_exp_f32_e32 v4, v4
	s_nop 0
	v_add_f32_e32 v4, 1.0, v4
	v_rcp_f32_e32 v4, v4
	s_nop 0
	v_mul_f32_e32 v4, v5, v4
	v_bfe_u32 v5, v4, 16, 1
	v_add3_u32 v4, v4, v5, s63
	global_store_short_d16_hi v[2:3], v4, off offset:64
	s_waitcnt vmcnt(62)
	v_lshlrev_b32_e32 v4, 16, v137
	v_mul_f32_e32 v5, v26, v128
	v_mul_f32_e32 v5, v5, v4
	v_mul_f32_e32 v4, 0xbfb8aa3b, v4
	v_exp_f32_e32 v4, v4
	v_add_co_u32_e32 v2, vcc, s93, v2
	v_add_f32_e32 v4, 1.0, v4
	v_rcp_f32_e32 v4, v4
	v_addc_co_u32_e32 v3, vcc, 0, v3, vcc
	v_mul_f32_e32 v4, v5, v4
	v_bfe_u32 v5, v4, 16, 1
	v_add3_u32 v4, v4, v5, s63
	global_store_short_d16_hi v[2:3], v4, off
	v_lshlrev_b32_e32 v4, 16, v136
	v_mul_f32_e32 v5, v10, v128
	v_mul_f32_e32 v5, v5, v4
	v_mul_f32_e32 v4, 0xbfb8aa3b, v4
	v_exp_f32_e32 v4, v4
	s_nop 0
	v_add_f32_e32 v4, 1.0, v4
	v_rcp_f32_e32 v4, v4
	s_nop 0
	v_mul_f32_e32 v4, v5, v4
	v_bfe_u32 v5, v4, 16, 1
	v_add3_u32 v4, v4, v5, s63
	global_store_short_d16_hi v[2:3], v4, off offset:64
	s_waitcnt vmcnt(62)
	v_lshlrev_b32_e32 v2, 16, v135
	v_mul_f32_e32 v3, v59, v122
	v_mul_f32_e32 v3, v3, v2
	v_mul_f32_e32 v2, 0xbfb8aa3b, v2
	v_exp_f32_e32 v2, v2
	v_mul_f32_e32 v5, v43, v122
	v_add_f32_e32 v2, 1.0, v2
	v_rcp_f32_e32 v2, v2
	s_nop 0
	v_mul_f32_e32 v2, v3, v2
	v_bfe_u32 v3, v2, 16, 1
	v_add3_u32 v4, v2, v3, s63
	v_lshlrev_b64 v[2:3], 7, v[80:81]
	v_lshl_add_u64 v[2:3], s[40:41], 0, v[2:3]
	v_lshl_add_u64 v[2:3], v[2:3], 0, v[66:67]
	global_store_short_d16_hi v[2:3], v4, off
	v_lshlrev_b32_e32 v4, 16, v134
	v_mul_f32_e32 v5, v5, v4
	v_mul_f32_e32 v4, 0xbfb8aa3b, v4
	v_exp_f32_e32 v4, v4
	s_nop 0
	v_add_f32_e32 v4, 1.0, v4
	v_rcp_f32_e32 v4, v4
	s_nop 0
	v_mul_f32_e32 v4, v5, v4
	v_bfe_u32 v5, v4, 16, 1
	v_add3_u32 v4, v4, v5, s63
	global_store_short_d16_hi v[2:3], v4, off offset:64
	s_waitcnt vmcnt(62)
	v_lshlrev_b32_e32 v4, 16, v132
	v_mul_f32_e32 v5, v27, v122
	v_mul_f32_e32 v5, v5, v4
	v_mul_f32_e32 v4, 0xbfb8aa3b, v4
	v_exp_f32_e32 v4, v4
	v_add_co_u32_e32 v2, vcc, s93, v2
	v_add_f32_e32 v4, 1.0, v4
	v_rcp_f32_e32 v4, v4
	v_addc_co_u32_e32 v3, vcc, 0, v3, vcc
	v_mul_f32_e32 v4, v5, v4
	v_bfe_u32 v5, v4, 16, 1
	v_add3_u32 v4, v4, v5, s63
	global_store_short_d16_hi v[2:3], v4, off
	v_lshlrev_b32_e32 v4, 16, v131
	v_mul_f32_e32 v5, v11, v122
	v_mul_f32_e32 v5, v5, v4
	v_mul_f32_e32 v4, 0xbfb8aa3b, v4
	v_exp_f32_e32 v4, v4
	s_nop 0
	v_add_f32_e32 v4, 1.0, v4
	v_rcp_f32_e32 v4, v4
	s_nop 0
	v_mul_f32_e32 v4, v5, v4
	v_bfe_u32 v5, v4, 16, 1
	v_add3_u32 v4, v4, v5, s63
	global_store_short_d16_hi v[2:3], v4, off offset:64
	s_waitcnt vmcnt(62)
	v_lshlrev_b32_e32 v2, 16, v130
	v_mul_f32_e32 v3, v60, v117
	v_mul_f32_e32 v3, v3, v2
	v_mul_f32_e32 v2, 0xbfb8aa3b, v2
	v_exp_f32_e32 v2, v2
	v_mul_f32_e32 v5, v44, v117
	v_add_f32_e32 v2, 1.0, v2
	v_rcp_f32_e32 v2, v2
	s_nop 0
	v_mul_f32_e32 v2, v3, v2
	v_bfe_u32 v3, v2, 16, 1
	v_add3_u32 v4, v2, v3, s63
	v_lshlrev_b64 v[2:3], 7, v[78:79]
	v_lshl_add_u64 v[2:3], s[40:41], 0, v[2:3]
	v_lshl_add_u64 v[2:3], v[2:3], 0, v[66:67]
	global_store_short_d16_hi v[2:3], v4, off
	v_lshlrev_b32_e32 v4, 16, v129
	v_mul_f32_e32 v5, v5, v4
	v_mul_f32_e32 v4, 0xbfb8aa3b, v4
	v_exp_f32_e32 v4, v4
	s_nop 0
	v_add_f32_e32 v4, 1.0, v4
	v_rcp_f32_e32 v4, v4
	s_nop 0
	v_mul_f32_e32 v4, v5, v4
	v_bfe_u32 v5, v4, 16, 1
	v_add3_u32 v4, v4, v5, s63
	global_store_short_d16_hi v[2:3], v4, off offset:64
	s_waitcnt vmcnt(62)
; __device__ __forceinline__ float bf2f(unsigned h) { return __uint_as_float(h << 16); }
; __device__ __forceinline__ unsigned f2bf(float f) { unsigned u = __float_as_uint(f); return (u + 0x7fffu + ((u >> 16) & 1u)) >> 16; }
; __device__ __forceinline__ int crow(int r, int hi) { return (r & 3) + 8 * (r >> 2) + 4 * hi; }
; __device__ __forceinline__ void mla_unit(char* lds, const bf16_t* __restrict__ Qp, const bf16_t* __restrict__ Knp, const bf16_t* __restrict__ Vp, ...
;     ...
;     for (int r = 0; r < 16; ++r) { const long trow = wid * QBLK + crow(r, hi);
; #pragma unroll
;       for (int d0 = 0; d0 < 4; ++d0) { const float z = bf2f(zr[r][d0]); const float v = o[d0][r] * rli[r];
;         const float g = v * z * __builtin_amdgcn_rcpf(1.f + __expf(-z));
;         Op[((size_t)(d0 >> 1) * M_TOK + trow) * 64 + (d0 & 1) * 32 + r32] = (bf16_t)f2bf(g); } } }
	v_lshlrev_b32_e32 v4, 16, v127
	v_mul_f32_e32 v5, v28, v117
	v_mul_f32_e32 v5, v5, v4
	v_mul_f32_e32 v4, 0xbfb8aa3b, v4
	v_exp_f32_e32 v4, v4
	v_add_co_u32_e32 v2, vcc, s93, v2
	v_add_f32_e32 v4, 1.0, v4
	v_rcp_f32_e32 v4, v4
	v_addc_co_u32_e32 v3, vcc, 0, v3, vcc
	v_mul_f32_e32 v4, v5, v4
	v_bfe_u32 v5, v4, 16, 1
	v_add3_u32 v4, v4, v5, s63
	global_store_short_d16_hi v[2:3], v4, off
	v_lshlrev_b32_e32 v4, 16, v126
	v_mul_f32_e32 v5, v12, v117
	v_mul_f32_e32 v5, v5, v4
	v_mul_f32_e32 v4, 0xbfb8aa3b, v4
	v_exp_f32_e32 v4, v4
	s_nop 0
	v_add_f32_e32 v4, 1.0, v4
	v_rcp_f32_e32 v4, v4
	s_nop 0
	v_mul_f32_e32 v4, v5, v4
	v_bfe_u32 v5, v4, 16, 1
	v_add3_u32 v4, v4, v5, s63
	global_store_short_d16_hi v[2:3], v4, off offset:64
	s_waitcnt vmcnt(62)
	v_lshlrev_b32_e32 v2, 16, v125
	v_mul_f32_e32 v3, v61, v111
	v_mul_f32_e32 v3, v3, v2
	v_mul_f32_e32 v2, 0xbfb8aa3b, v2
	v_exp_f32_e32 v2, v2
	v_mul_f32_e32 v5, v45, v111
	v_add_f32_e32 v2, 1.0, v2
	v_rcp_f32_e32 v2, v2
	s_nop 0
	v_mul_f32_e32 v2, v3, v2
	v_bfe_u32 v3, v2, 16, 1
	v_add3_u32 v4, v2, v3, s63
	v_lshlrev_b64 v[2:3], 7, v[76:77]
	v_lshl_add_u64 v[2:3], s[40:41], 0, v[2:3]
	v_lshl_add_u64 v[2:3], v[2:3], 0, v[66:67]
	global_store_short_d16_hi v[2:3], v4, off
	v_lshlrev_b32_e32 v4, 16, v124
	v_mul_f32_e32 v5, v5, v4
	v_mul_f32_e32 v4, 0xbfb8aa3b, v4
	v_exp_f32_e32 v4, v4
	s_nop 0
	v_add_f32_e32 v4, 1.0, v4
	v_rcp_f32_e32 v4, v4
	s_nop 0
	v_mul_f32_e32 v4, v5, v4
	v_bfe_u32 v5, v4, 16, 1
	v_add3_u32 v4, v4, v5, s63
	global_store_short_d16_hi v[2:3], v4, off offset:64
	s_waitcnt vmcnt(62)
	v_lshlrev_b32_e32 v4, 16, v123
	v_mul_f32_e32 v5, v29, v111
	v_mul_f32_e32 v5, v5, v4
	v_mul_f32_e32 v4, 0xbfb8aa3b, v4
	v_exp_f32_e32 v4, v4
	v_add_co_u32_e32 v2, vcc, s93, v2
	v_add_f32_e32 v4, 1.0, v4
	v_rcp_f32_e32 v4, v4
	v_addc_co_u32_e32 v3, vcc, 0, v3, vcc
	v_mul_f32_e32 v4, v5, v4
	v_bfe_u32 v5, v4, 16, 1
	v_add3_u32 v4, v4, v5, s63
	global_store_short_d16_hi v[2:3], v4, off
	v_lshlrev_b32_e32 v4, 16, v121
	v_mul_f32_e32 v5, v13, v111
	v_mul_f32_e32 v5, v5, v4
	v_mul_f32_e32 v4, 0xbfb8aa3b, v4
	v_exp_f32_e32 v4, v4
	s_nop 0
	v_add_f32_e32 v4, 1.0, v4
	v_rcp_f32_e32 v4, v4
	s_nop 0
	v_mul_f32_e32 v4, v5, v4
	v_bfe_u32 v5, v4, 16, 1
	v_add3_u32 v4, v4, v5, s63
	global_store_short_d16_hi v[2:3], v4, off offset:64
	s_waitcnt vmcnt(62)
	v_lshlrev_b32_e32 v2, 16, v120
	v_mul_f32_e32 v3, v62, v105
	v_mul_f32_e32 v3, v3, v2
	v_mul_f32_e32 v2, 0xbfb8aa3b, v2
	v_exp_f32_e32 v2, v2
	v_mul_f32_e32 v5, v46, v105
	v_add_f32_e32 v2, 1.0, v2
	v_rcp_f32_e32 v2, v2
	s_nop 0
	v_mul_f32_e32 v2, v3, v2
	v_bfe_u32 v3, v2, 16, 1
	v_add3_u32 v4, v2, v3, s63
	v_lshlrev_b64 v[2:3], 7, v[74:75]
	v_lshl_add_u64 v[2:3], s[40:41], 0, v[2:3]
	v_lshl_add_u64 v[2:3], v[2:3], 0, v[66:67]
	global_store_short_d16_hi v[2:3], v4, off
	v_lshlrev_b32_e32 v4, 16, v119
	v_mul_f32_e32 v5, v5, v4
	v_mul_f32_e32 v4, 0xbfb8aa3b, v4
	v_exp_f32_e32 v4, v4
	s_nop 0
	v_add_f32_e32 v4, 1.0, v4
	v_rcp_f32_e32 v4, v4
	s_nop 0
	v_mul_f32_e32 v4, v5, v4
	v_bfe_u32 v5, v4, 16, 1
	v_add3_u32 v4, v4, v5, s63
	global_store_short_d16_hi v[2:3], v4, off offset:64
	s_waitcnt vmcnt(62)
	v_lshlrev_b32_e32 v4, 16, v118
	v_mul_f32_e32 v5, v30, v105
	v_mul_f32_e32 v5, v5, v4
	v_mul_f32_e32 v4, 0xbfb8aa3b, v4
	v_exp_f32_e32 v4, v4
	v_add_co_u32_e32 v2, vcc, s93, v2
	v_add_f32_e32 v4, 1.0, v4
	v_rcp_f32_e32 v4, v4
	v_addc_co_u32_e32 v3, vcc, 0, v3, vcc
	v_mul_f32_e32 v4, v5, v4
	v_bfe_u32 v5, v4, 16, 1
	v_add3_u32 v4, v4, v5, s63
	global_store_short_d16_hi v[2:3], v4, off
	v_lshlrev_b32_e32 v4, 16, v116
	v_mul_f32_e32 v5, v14, v105
	v_mul_f32_e32 v5, v5, v4
	v_mul_f32_e32 v4, 0xbfb8aa3b, v4
	v_exp_f32_e32 v4, v4
	s_nop 0
	v_add_f32_e32 v4, 1.0, v4
	v_rcp_f32_e32 v4, v4
	s_nop 0
	v_mul_f32_e32 v4, v5, v4
	v_bfe_u32 v5, v4, 16, 1
	v_add3_u32 v4, v4, v5, s63
	global_store_short_d16_hi v[2:3], v4, off offset:64
	s_waitcnt vmcnt(62)
	v_lshlrev_b32_e32 v2, 16, v115
	v_mul_f32_e32 v3, v63, v103
	v_mul_f32_e32 v3, v3, v2
	v_mul_f32_e32 v2, 0xbfb8aa3b, v2
	v_exp_f32_e32 v2, v2
	v_mul_f32_e32 v5, v47, v103
	v_add_f32_e32 v2, 1.0, v2
	v_rcp_f32_e32 v2, v2
	s_nop 0
	v_mul_f32_e32 v2, v3, v2
	v_bfe_u32 v3, v2, 16, 1
	v_add3_u32 v4, v2, v3, s63
	v_lshlrev_b64 v[2:3], 7, v[72:73]
	v_lshl_add_u64 v[2:3], s[40:41], 0, v[2:3]
	v_lshl_add_u64 v[2:3], v[2:3], 0, v[66:67]
	global_store_short_d16_hi v[2:3], v4, off
	v_lshlrev_b32_e32 v4, 16, v114
	v_mul_f32_e32 v5, v5, v4
	v_mul_f32_e32 v4, 0xbfb8aa3b, v4
	v_exp_f32_e32 v4, v4
	s_nop 0
	v_add_f32_e32 v4, 1.0, v4
	v_rcp_f32_e32 v4, v4
	s_nop 0
	v_mul_f32_e32 v4, v5, v4
	v_bfe_u32 v5, v4, 16, 1
	v_add3_u32 v4, v4, v5, s63
	global_store_short_d16_hi v[2:3], v4, off offset:64
	s_waitcnt vmcnt(62)
	v_lshlrev_b32_e32 v4, 16, v113
	v_mul_f32_e32 v5, v31, v103
	v_mul_f32_e32 v5, v5, v4
	v_mul_f32_e32 v4, 0xbfb8aa3b, v4
	v_exp_f32_e32 v4, v4
	v_add_co_u32_e32 v2, vcc, s93, v2
	v_add_f32_e32 v4, 1.0, v4
	v_rcp_f32_e32 v4, v4
	v_addc_co_u32_e32 v3, vcc, 0, v3, vcc
	v_mul_f32_e32 v4, v5, v4
	v_bfe_u32 v5, v4, 16, 1
	v_add3_u32 v4, v4, v5, s63
	global_store_short_d16_hi v[2:3], v4, off
	v_lshlrev_b32_e32 v4, 16, v112
	v_mul_f32_e32 v5, v15, v103
	v_mul_f32_e32 v5, v5, v4
	v_mul_f32_e32 v4, 0xbfb8aa3b, v4
	v_exp_f32_e32 v4, v4
	s_nop 0
	v_add_f32_e32 v4, 1.0, v4
	v_rcp_f32_e32 v4, v4
	s_nop 0
	v_mul_f32_e32 v4, v5, v4
	v_bfe_u32 v5, v4, 16, 1
	v_add3_u32 v4, v4, v5, s63
	global_store_short_d16_hi v[2:3], v4, off offset:64
	s_waitcnt vmcnt(62)
; __device__ __forceinline__ int opaque_tid() { int t = threadIdx.x; asm volatile("" : "+v"(t)); return t; }
; __device__ __forceinline__ float bf2f(unsigned h) { return __uint_as_float(h << 16); }
; __device__ __forceinline__ unsigned f2bf(float f) { unsigned u = __float_as_uint(f); return (u + 0x7fffu + ((u >> 16) & 1u)) >> 16; }
; __device__ __forceinline__ int crow(int r, int hi) { return (r & 3) + 8 * (r >> 2) + 4 * hi; }
; __device__ __forceinline__ void mla_unit(char* lds, const bf16_t* __restrict__ Qp, const bf16_t* __restrict__ Knp, const bf16_t* __restrict__ Vp, ...
;     ...
;   const int tid = opaque_tid(), wid = __builtin_amdgcn_readfirstlane(tid >> 6), lane = tid & 63, r32 = lane & 31, hi = lane >> 5;
;     ...
;     for (int r = 0; r < 16; ++r) { const long trow = wid * QBLK + crow(r, hi);
; #pragma unroll
;       for (int d0 = 0; d0 < 4; ++d0) { const float z = bf2f(zr[r][d0]); const float v = o[d0][r] * rli[r];
;         const float g = v * z * __builtin_amdgcn_rcpf(1.f + __expf(-z));
;         Op[((size_t)(d0 >> 1) * M_TOK + trow) * 64 + (d0 & 1) * 32 + r32] = (bf16_t)f2bf(g); } } }
;   asm volatile("s_waitcnt vmcnt(0) lgkmcnt(0)\n\ts_barrier" ::: "memory");
	v_lshlrev_b32_e32 v2, 16, v110
	v_mul_f32_e32 v3, v64, v102
	v_mul_f32_e32 v3, v3, v2
	v_mul_f32_e32 v2, 0xbfb8aa3b, v2
	v_exp_f32_e32 v2, v2
	v_mul_f32_e32 v5, v48, v102
	v_add_f32_e32 v2, 1.0, v2
	v_rcp_f32_e32 v2, v2
	s_nop 0
	v_mul_f32_e32 v2, v3, v2
	v_bfe_u32 v3, v2, 16, 1
	v_add3_u32 v4, v2, v3, s63
	v_lshlrev_b64 v[2:3], 7, v[70:71]
	v_lshl_add_u64 v[2:3], s[40:41], 0, v[2:3]
	v_lshl_add_u64 v[2:3], v[2:3], 0, v[66:67]
	global_store_short_d16_hi v[2:3], v4, off
	v_lshlrev_b32_e32 v4, 16, v109
	v_mul_f32_e32 v5, v5, v4
	v_mul_f32_e32 v4, 0xbfb8aa3b, v4
	v_exp_f32_e32 v4, v4
	s_nop 0
	v_add_f32_e32 v4, 1.0, v4
	v_rcp_f32_e32 v4, v4
	s_nop 0
	v_mul_f32_e32 v4, v5, v4
	v_bfe_u32 v5, v4, 16, 1
	v_add3_u32 v4, v4, v5, s63
	global_store_short_d16_hi v[2:3], v4, off offset:64
	s_waitcnt vmcnt(62)
	v_lshlrev_b32_e32 v4, 16, v108
	v_mul_f32_e32 v5, v32, v102
	v_mul_f32_e32 v5, v5, v4
	v_mul_f32_e32 v4, 0xbfb8aa3b, v4
	v_exp_f32_e32 v4, v4
	v_add_co_u32_e32 v2, vcc, s93, v2
	v_add_f32_e32 v4, 1.0, v4
	v_rcp_f32_e32 v4, v4
	v_addc_co_u32_e32 v3, vcc, 0, v3, vcc
	v_mul_f32_e32 v4, v5, v4
	v_bfe_u32 v5, v4, 16, 1
	v_add3_u32 v4, v4, v5, s63
	global_store_short_d16_hi v[2:3], v4, off
	v_lshlrev_b32_e32 v4, 16, v107
	v_mul_f32_e32 v5, v16, v102
	v_mul_f32_e32 v5, v5, v4
	v_mul_f32_e32 v4, 0xbfb8aa3b, v4
	v_exp_f32_e32 v4, v4
	s_nop 0
	v_add_f32_e32 v4, 1.0, v4
	v_rcp_f32_e32 v4, v4
	s_nop 0
	v_mul_f32_e32 v4, v5, v4
	v_bfe_u32 v5, v4, 16, 1
	v_add3_u32 v4, v4, v5, s63
	global_store_short_d16_hi v[2:3], v4, off offset:64
	s_waitcnt vmcnt(62)
	v_lshlrev_b32_e32 v2, 16, v106
	v_mul_f32_e32 v3, v65, v1
	v_mul_f32_e32 v3, v3, v2
	v_mul_f32_e32 v2, 0xbfb8aa3b, v2
	v_exp_f32_e32 v2, v2
	v_mul_f32_e32 v5, v49, v1
	v_add_f32_e32 v2, 1.0, v2
	v_rcp_f32_e32 v2, v2
	s_nop 0
	v_mul_f32_e32 v2, v3, v2
	v_bfe_u32 v3, v2, 16, 1
	v_add3_u32 v4, v2, v3, s63
	v_lshlrev_b64 v[2:3], 7, v[68:69]
	v_lshl_add_u64 v[2:3], s[40:41], 0, v[2:3]
	v_lshl_add_u64 v[2:3], v[2:3], 0, v[66:67]
	global_store_short_d16_hi v[2:3], v4, off
	v_lshlrev_b32_e32 v4, 16, v104
	v_mul_f32_e32 v5, v5, v4
	v_mul_f32_e32 v4, 0xbfb8aa3b, v4
	v_exp_f32_e32 v4, v4
	s_nop 0
	v_add_f32_e32 v4, 1.0, v4
	v_rcp_f32_e32 v4, v4
	s_nop 0
	v_mul_f32_e32 v4, v5, v4
	v_bfe_u32 v5, v4, 16, 1
	v_add3_u32 v4, v4, v5, s63
	global_store_short_d16_hi v[2:3], v4, off offset:64
	s_waitcnt vmcnt(62)
	v_lshlrev_b32_e32 v4, 16, v101
	v_mul_f32_e32 v5, v33, v1
	v_mul_f32_e32 v5, v5, v4
	v_mul_f32_e32 v4, 0xbfb8aa3b, v4
	v_exp_f32_e32 v4, v4
	v_add_co_u32_e32 v2, vcc, s93, v2
	v_mul_f32_e32 v1, v17, v1
	v_add_f32_e32 v4, 1.0, v4
	v_rcp_f32_e32 v4, v4
	v_addc_co_u32_e32 v3, vcc, 0, v3, vcc
	s_and_b64 vcc, exec, s[42:43]
	v_mul_f32_e32 v4, v5, v4
	v_bfe_u32 v5, v4, 16, 1
	v_add3_u32 v4, v4, v5, s63
	global_store_short_d16_hi v[2:3], v4, off
	v_lshlrev_b32_e32 v4, 16, v100
	v_mul_f32_e32 v1, v1, v4
	v_mul_f32_e32 v4, 0xbfb8aa3b, v4
	v_exp_f32_e32 v4, v4
	s_nop 0
	v_add_f32_e32 v4, 1.0, v4
	v_rcp_f32_e32 v4, v4
	s_nop 0
	v_mul_f32_e32 v1, v1, v4
	v_bfe_u32 v4, v1, 16, 1
	v_add3_u32 v1, v1, v4, s63
	global_store_short_d16_hi v[2:3], v1, off offset:64
	s_setprio 0
	s_waitcnt vmcnt(0) lgkmcnt(0)
	s_barrier
	s_cbranch_vccnz .LBB0_271
.LBB0_236:
	v_mov_b32_e32 v50, v252
	s_ashr_i32 s6, s74, 9
	v_readfirstlane_b32 s0, v50
	s_ashr_i32 s8, s0, 6
	s_cmp_lt_u32 s8, 4
	s_cbranch_scc1 .Lmla_prio_skip
	s_setprio 1
; #define DMA_K(t, slot) do { const bf16_t* s_ = Knp + (long)(t) * (KVBLK * LDK); const unsigned d_ = (unsigned)__builtin_amdgcn_readfirstlane(kn_dst + (slot) * SHM_KN); \
;     glds16s(s_, kn_off, d_); glds16s(s_ + 16 * LDK, kn_off, d_ + 4096); glds16s(Krp + (long)(t) * (KVBLK * 64), kr_off, (unsigned)__builtin_amdgcn_readfirstlane(kr_dst + (slot) * SHM_KR)); } while (0)
; #define DMA_V(t, slot) do { const bf16_t* s_ = Vp + (long)(t) * (KVBLK * LDK); const unsigned d_ = (unsigned)__builtin_amdgcn_readfirstlane(v_dst + (slot) * SHM_V); \
;     glds16s(s_, v_off, d_); glds16s(s_ + 32 * LDK, v_off, d_ + 8192); } while (0)
; __device__ __forceinline__ void mla_unit(char* lds, const bf16_t* __restrict__ Qp, const bf16_t* __restrict__ Knp, const bf16_t* __restrict__ Vp, ...
;     ...
;   const int pk = (wid & 3) + 8 * (wid >> 2);
;   const int krow_n = 4 * pk + (lane >> 4);
;   const unsigned kn_off = (unsigned)(krow_n * LDK + (((lane & 15) ^ (krow_n & 15)) << 3)) * 2u;
;   const int krow_r = 8 * wid + (lane >> 3);
;   const unsigned kr_off = (unsigned)(krow_r * 64 + (((lane & 7) ^ ((krow_r >> 1) & 7)) << 3)) * 2u;
;   const int vst_ = 2 * wid + (lane >> 5), vkk = (vst_ >> 2) * 8 + ((lane >> 2) & 7), vkey = (vkk & ~0xC) | ((vkk & 4) << 1) | ((vkk & 8) >> 1), vcol = (vst_ & 3) * 32 + (lane & 3) * 8;
;   const unsigned v_off = (unsigned)(vkey * LDK + vcol) * 2u;
;   const unsigned kn_dst = lds0 + P_KN + pk * 1024, kr_dst = lds0 + P_KR + wid * 1024, v_dst = lds0 + P_V + wid * 1024;
;     ...
;   if (first) { DMA_K(0, 0); DMA_V(0, 0); DMA_K(1, 1); DMA_V(1, 1); DMA_K(2, 2); }
.Lmla_prio_skip:
	s_ashr_i32 s5, s0, 5
	s_and_b32 s1, s8, 3
	s_and_b32 s5, s5, -8
	s_or_b32 s1, s1, s5
	s_lshl_b32 s5, s1, 2
	s_ashr_i32 s12, s0, 4
	v_bfe_u32 v1, v50, 4, 2
	s_ashr_i32 s7, s6, 31
	s_and_b32 s13, s12, 0x7ffff0
	s_lshr_b32 s12, s12, 1
	v_or_b32_e32 v2, s5, v1
	v_bitop3_b32 v1, s5, v50, v1 bitop3:0x36
	s_bfe_u32 s38, s74, 0x40005
	s_lshl_b64 s[30:31], s[6:7], 22
	s_lshl_b64 s[36:37], s[6:7], 20
	s_lshl_b32 s9, s8, 1
	s_and_b32 s12, s12, 4
	s_lshl_b32 s72, s1, 10
	v_lshlrev_b32_e32 v2, 9, v2
	v_lshlrev_b32_e32 v1, 4, v1
	s_cmp_lg_u32 0, -1
	v_and_or_b32 v197, v1, s53, v2
	v_bfe_u32 v1, v50, 3, 3
	s_cselect_b32 s1, 0, 0
	s_lshl_b32 s71, s8, 10
	v_lshl_or_b32 v1, s8, 3, v1
	s_add_i32 s14, s1, s72
	s_add_i32 s73, s71, s1
	v_lshlrev_b32_e32 v2, 7, v1
	v_lshrrev_b32_e32 v1, 1, v1
	s_add_i32 s76, s14, 0xc000
	s_add_i32 s75, s73, 0x18000
	v_readlane_b32 s1, v253, 3
	v_xor_b32_e32 v1, v1, v50
	s_cmp_lg_u32 s74, s1
	v_lshlrev_b32_e32 v1, 4, v1
	s_movk_i32 s1, 0x70
	v_and_or_b32 v198, v1, s1, v2
	v_lshrrev_b32_e32 v1, 2, v50
	v_lshrrev_b32_e32 v2, 1, v50
	v_bfe_u32 v49, v50, 5, 1
	v_and_or_b32 v1, v1, 3, s13
	v_and_b32_e32 v2, 8, v2
	v_lshlrev_b32_e32 v48, 4, v50
	v_or3_b32 v1, v1, v2, s12
	v_and_or_b32 v2, s9, 2, v49
	v_and_b32_e32 v3, 48, v48
	v_lshl_or_b32 v2, v2, 6, v3
	v_lshl_or_b32 v199, v1, 9, v2
	s_cbranch_scc1 .LBB0_238
	s_lshl_b32 s1, s38, 23
	v_readlane_b32 s5, v254, 62
	s_add_u32 s1, s5, s1
	v_readlane_b32 s5, v254, 63
	s_addc_u32 s5, s5, 0
	s_add_u32 s12, s1, s30
	s_addc_u32 s13, s5, s31
	s_add_u32 s14, s12, 0x100
	s_addc_u32 s15, s13, 0
	s_add_u32 s16, s26, s36
	s_addc_u32 s17, s27, s37
	s_mov_b32 s1, m0
	s_mov_b32 m0, s76
	s_nop 0
	global_load_lds_dwordx4 v197, s[12:13]
	s_mov_b32 m0, s1
	s_add_u32 s18, s12, 0x2000
	s_addc_u32 s19, s13, 0
	s_add_i32 s1, s76, 0x1000
	s_mov_b32 s5, m0
	s_mov_b32 m0, s1
	s_nop 0
	global_load_lds_dwordx4 v197, s[18:19]
	s_mov_b32 m0, s5
	s_mov_b32 s1, m0
	s_mov_b32 m0, s75
	s_nop 0
	global_load_lds_dwordx4 v198, s[16:17]
	s_mov_b32 m0, s1
	s_nop 0
	s_mov_b32 s1, m0
	s_mov_b32 m0, s73
	s_nop 0
	global_load_lds_dwordx4 v199, s[14:15]
	s_mov_b32 m0, s1
	s_add_u32 s14, s12, 0x4100
	s_addc_u32 s15, s13, 0
	s_add_i32 s1, s73, 0x2000
	s_mov_b32 s5, m0
	s_mov_b32 m0, s1
	s_nop 0
	global_load_lds_dwordx4 v199, s[14:15]
	s_mov_b32 m0, s5
	s_add_u32 s14, s12, 0x8000
	s_addc_u32 s15, s13, 0
	s_cmp_lg_u32 0, -1
	s_cselect_b32 s1, 0, 0
	s_add_i32 s5, s1, s72
	s_add_i32 s9, s5, 0x10000
	s_mov_b32 s18, m0
	s_mov_b32 m0, s9
	s_nop 0
	global_load_lds_dwordx4 v197, s[14:15]
	s_mov_b32 m0, s18
	s_add_u32 s14, s12, 0xa000
	s_addc_u32 s15, s13, 0
	s_add_i32 s9, s5, 0x11000
	s_mov_b32 s18, m0
	s_mov_b32 m0, s9
	s_nop 0
	global_load_lds_dwordx4 v197, s[14:15]
	s_mov_b32 m0, s18
	s_add_u32 s14, s16, 0x2000
	s_addc_u32 s15, s17, 0
	s_add_i32 s1, s1, s71
	s_add_i32 s9, s1, 0x1a000
	s_mov_b32 s18, m0
	s_mov_b32 m0, s9
	s_nop 0
	global_load_lds_dwordx4 v198, s[14:15]
	s_mov_b32 m0, s18
	s_add_u32 s14, s12, 0x8100
	s_addc_u32 s15, s13, 0
	s_add_i32 s9, s1, 0x4000
	s_mov_b32 s18, m0
	s_mov_b32 m0, s9
	s_nop 0
	global_load_lds_dwordx4 v199, s[14:15]
	s_mov_b32 m0, s18
	s_add_u32 s14, s12, 0xc100
	s_addc_u32 s15, s13, 0
	s_add_i32 s9, s1, 0x6000
	s_mov_b32 s18, m0
	s_mov_b32 m0, s9
	s_nop 0
	global_load_lds_dwordx4 v199, s[14:15]
	s_mov_b32 m0, s18
	s_add_u32 s14, s12, 0x10000
	s_addc_u32 s15, s13, 0
	s_add_i32 s9, s5, 0x14000
	s_add_u32 s12, s12, 0x12000
	s_mov_b32 s18, m0
	s_mov_b32 m0, s9
	s_nop 0
	global_load_lds_dwordx4 v197, s[14:15]
	s_mov_b32 m0, s18
	s_addc_u32 s13, s13, 0
	s_add_i32 s5, s5, 0x15000
	s_mov_b32 s9, m0
	s_mov_b32 m0, s5
	s_nop 0
	global_load_lds_dwordx4 v197, s[12:13]
	s_mov_b32 m0, s9
	s_add_u32 s12, s16, 0x4000
	s_addc_u32 s13, s17, 0
	s_add_i32 s1, s1, 0x1c000
	s_mov_b32 s5, m0
	s_mov_b32 m0, s1
	s_nop 0
	global_load_lds_dwordx4 v198, s[12:13]
	s_mov_b32 m0, s5
